# speedup vs baseline: 1.0082x; 1.0016x over previous
; DI int tid_() { int t = threadIdx.x; asm volatile("" : "+v"(t)); return t; }
; DI int bid_() { int b = blockIdx.x; asm volatile("" : "+s"(b)); return b; }
; DI void phase_hg2(const Params& p, int L) {
;     ...
;   for (int idx = bid_() * 512 + tid_(); idx < ncombo * 16384; idx += gridDim.x * 512) {
;     const int combo = idx >> 14, e = idx & 16383, k = e >> 7; const int dir = (combo >> 3) & 1;
;     const long s_st = dir ? -16384 : 16384; const int s_pv = dir ? -128 : 128;
;     float* sp = ST + ((size_t)combo * nsc + (dir ? nsc - 1 : 0)) * 16384 + e;
;     const float* pp = PV + ((size_t)combo * nsc + (dir ? nsc - 1 : 0)) * 128 + k;
;     float carry = 0.f;
;     for (int j0 = 0; j0 < nsc; j0 += 8) {
;       float tmp[8], pv[8];
; #pragma unroll
;       for (int u = 0; u < 8; ++u) { tmp[u] = sp[u * s_st]; pv[u] = pp[u * s_pv]; }
; #pragma unroll
;       for (int u = 0; u < 8; ++u) { sp[u * s_st] = carry; carry = pv[u] * carry + tmp[u]; }
;       sp += 8 * s_st; pp += 8 * s_pv;
;     }
;   }
.LBB0_90:
	v_lshl_add_u64 v[28:29], s[26:27], 0, v[2:3]
	v_lshl_add_u64 v[30:31], s[26:27], 0, v[6:7]
	global_load_dword v27, v[30:31], off nt
	global_load_dword v46, v[28:29], off
	v_lshl_add_u64 v[32:33], s[26:27], 0, v[22:23]
	v_lshl_add_u64 v[28:29], v[28:29], 0, v[0:1]
	global_load_dword v47, v[32:33], off nt
	global_load_dword v48, v[28:29], off
	v_lshl_add_u64 v[34:35], s[26:27], 0, v[10:11]
	v_lshl_add_u64 v[28:29], v[28:29], 0, v[0:1]
	global_load_dword v49, v[34:35], off nt
	global_load_dword v50, v[28:29], off
	v_lshl_add_u64 v[36:37], s[26:27], 0, v[12:13]
	v_lshl_add_u64 v[28:29], v[28:29], 0, v[0:1]
	global_load_dword v51, v[36:37], off nt
	global_load_dword v52, v[28:29], off
	v_lshl_add_u64 v[38:39], s[26:27], 0, v[14:15]
	v_lshl_add_u64 v[28:29], v[28:29], 0, v[0:1]
	global_load_dword v53, v[38:39], off nt
	global_load_dword v54, v[28:29], off
	v_lshl_add_u64 v[40:41], s[26:27], 0, v[16:17]
	v_lshl_add_u64 v[28:29], v[28:29], 0, v[0:1]
	global_load_dword v55, v[40:41], off nt
	global_load_dword v56, v[28:29], off
	v_lshl_add_u64 v[42:43], s[26:27], 0, v[18:19]
	v_lshl_add_u64 v[28:29], v[28:29], 0, v[0:1]
	global_load_dword v57, v[42:43], off nt
	global_load_dword v58, v[28:29], off
	v_lshl_add_u64 v[44:45], s[26:27], 0, v[20:21]
	v_lshl_add_u64 v[28:29], v[28:29], 0, v[0:1]
	global_load_dword v59, v[44:45], off nt
	s_add_i32 s40, s40, 8
	global_load_dword v28, v[28:29], off
	v_lshl_add_u64 v[2:3], v[2:3], 0, v[4:5]
	global_store_dword v[30:31], v26, off nt
	v_lshl_add_u64 v[6:7], v[6:7], 0, v[8:9]
	v_lshl_add_u64 v[10:11], v[10:11], 0, v[8:9]
	v_lshl_add_u64 v[12:13], v[12:13], 0, v[8:9]
	v_lshl_add_u64 v[14:15], v[14:15], 0, v[8:9]
	v_lshl_add_u64 v[16:17], v[16:17], 0, v[8:9]
	v_lshl_add_u64 v[18:19], v[18:19], 0, v[8:9]
	v_lshl_add_u64 v[20:21], v[20:21], 0, v[8:9]
	v_lshl_add_u64 v[22:23], v[22:23], 0, v[8:9]
	s_cmp_lt_u32 s40, s7
	s_waitcnt vmcnt(15)
	v_fmac_f32_e32 v27, v26, v46
	global_store_dword v[32:33], v27, off nt
	s_waitcnt vmcnt(14)
	v_fmac_f32_e32 v47, v27, v48
	global_store_dword v[34:35], v47, off nt
	s_waitcnt vmcnt(13)
	v_fmac_f32_e32 v49, v47, v50
	global_store_dword v[36:37], v49, off nt
	s_waitcnt vmcnt(12)
	v_fmac_f32_e32 v51, v49, v52
	global_store_dword v[38:39], v51, off nt
	s_waitcnt vmcnt(11)
	v_fmac_f32_e32 v53, v51, v54
	global_store_dword v[40:41], v53, off nt
	s_waitcnt vmcnt(10)
	v_fmac_f32_e32 v55, v53, v56
	global_store_dword v[42:43], v55, off nt
	s_waitcnt vmcnt(9)
	v_fmac_f32_e32 v57, v55, v58
	global_store_dword v[44:45], v57, off nt
	s_waitcnt vmcnt(8)
	v_fmac_f32_e32 v59, v57, v28
	v_mov_b32_e32 v26, v59
	s_cbranch_scc1 .LBB0_90
	v_add_u32_e32 v24, s58, v24
	v_cmp_le_i32_e32 vcc, s6, v24
	s_or_b64 s[38:39], vcc, s[38:39]
	v_add_u16_e32 v25, s58, v25
	s_andn2_b64 exec, exec, s[38:39]
	s_cbranch_execnz .LBB0_89
